# mlstm_local: chunk Q.K^T on the f32 matrix cores (v_mfma_f32_16x16x4_f32) instead of the packed-f32 VALU loop
# speedup vs baseline: 1.5636x; 1.0075x over previous
.LBB0_295:
	s_or_b64 exec, exec, s[94:95]
	v_ashrrev_i32_e32 v19, 4, v0
	v_and_b32_e32 v20, 15, v0
	v_mov_b32_e32 v3, 0
	v_cmp_le_i32_e32 vcc, v20, v19
	v_mov_b32_e32 v2, v3
	v_mov_b32_e32 v5, v3
	v_mov_b32_e32 v4, v3
	v_mov_b32_e32 v7, v3
	v_mov_b32_e32 v6, v3
	v_mov_b32_e32 v9, v3
	v_mov_b32_e32 v8, v3
	v_mov_b32_e32 v17, v3
	v_mov_b32_e32 v16, v3
	v_mov_b32_e32 v15, v3
	v_mov_b32_e32 v14, v3
	v_mov_b32_e32 v13, v3
	v_mov_b32_e32 v12, v3
	v_mov_b32_e32 v11, v3
	v_mov_b32_e32 v10, v3
	s_waitcnt lgkmcnt(0)
	s_barrier
	v_lshrrev_b32_e32 v18, 6, v182
	v_and_b32_e32 v21, 15, v182
	v_bfe_u32 v22, v182, 4, 2
	v_mul_u32_u24_e32 v23, 0x104, v21
	v_readfirstlane_b32 s0, v18
	v_lshl_add_u32 v23, v22, 2, v23
	v_mul_u32_u24_e32 v24, 0x1040, v18
	v_add_u32_e32 v26, v24, v23
	v_add_u32_e32 v28, 0x4100, v26
	ds_read2_b32 v[136:137], v26 offset0:0 offset1:4
	ds_read2_b32 v[138:139], v26 offset0:8 offset1:12
	ds_read2_b32 v[140:141], v26 offset0:16 offset1:20
	ds_read2_b32 v[142:143], v26 offset0:24 offset1:28
	ds_read2_b32 v[144:145], v26 offset0:32 offset1:36
	ds_read2_b32 v[146:147], v26 offset0:40 offset1:44
	ds_read2_b32 v[148:149], v26 offset0:48 offset1:52
	ds_read2_b32 v[150:151], v26 offset0:56 offset1:60
	ds_read2_b32 v[152:153], v28 offset0:0 offset1:4
	ds_read2_b32 v[154:155], v28 offset0:8 offset1:12
	ds_read2_b32 v[156:157], v28 offset0:16 offset1:20
	ds_read2_b32 v[158:159], v28 offset0:24 offset1:28
	ds_read2_b32 v[160:161], v28 offset0:32 offset1:36
	ds_read2_b32 v[162:163], v28 offset0:40 offset1:44
	ds_read2_b32 v[164:165], v28 offset0:48 offset1:52
	ds_read2_b32 v[166:167], v28 offset0:56 offset1:60
	v_lshlrev_b32_e32 v29, 12, v18
	v_lshl_add_u32 v29, v22, 10, v29
	v_add_u32_e32 v29, 0x9000, v29
	v_lshl_add_u32 v34, v21, 2, v29
	v_lshl_add_u32 v35, v21, 4, v29
	v_lshlrev_b32_e32 v37, 6, v18
	s_mov_b64 s[10:11], exec
	s_waitcnt lgkmcnt(0)
	v_mfma_f32_16x16x4_f32 v[224:227], v136, v152, 0
	v_mfma_f32_16x16x4_f32 v[224:227], v137, v153, v[224:227]
	v_mfma_f32_16x16x4_f32 v[224:227], v138, v154, v[224:227]
	v_mfma_f32_16x16x4_f32 v[224:227], v139, v155, v[224:227]
	v_mfma_f32_16x16x4_f32 v[224:227], v140, v156, v[224:227]
	v_mfma_f32_16x16x4_f32 v[224:227], v141, v157, v[224:227]
	v_mfma_f32_16x16x4_f32 v[224:227], v142, v158, v[224:227]
	v_mfma_f32_16x16x4_f32 v[224:227], v143, v159, v[224:227]
	v_mfma_f32_16x16x4_f32 v[224:227], v144, v160, v[224:227]
	v_mfma_f32_16x16x4_f32 v[224:227], v145, v161, v[224:227]
	v_mfma_f32_16x16x4_f32 v[224:227], v146, v162, v[224:227]
	v_mfma_f32_16x16x4_f32 v[224:227], v147, v163, v[224:227]
	v_mfma_f32_16x16x4_f32 v[224:227], v148, v164, v[224:227]
	v_mfma_f32_16x16x4_f32 v[224:227], v149, v165, v[224:227]
	v_mfma_f32_16x16x4_f32 v[224:227], v150, v166, v[224:227]
	v_mfma_f32_16x16x4_f32 v[224:227], v151, v167, v[224:227]
	s_cmp_lt_u32 s0, 1
	s_cbranch_scc1 .Lmqk_md
	v_add_u32_e32 v36, 0xffffefc0, v28
	ds_read2_b32 v[116:117], v36 offset0:0 offset1:4
	ds_read2_b32 v[118:119], v36 offset0:8 offset1:12
	ds_read2_b32 v[120:121], v36 offset0:16 offset1:20
	ds_read2_b32 v[122:123], v36 offset0:24 offset1:28
	ds_read2_b32 v[124:125], v36 offset0:32 offset1:36
	ds_read2_b32 v[126:127], v36 offset0:40 offset1:44
	ds_read2_b32 v[128:129], v36 offset0:48 offset1:52
	ds_read2_b32 v[130:131], v36 offset0:56 offset1:60
	s_waitcnt lgkmcnt(0)
	v_mfma_f32_16x16x4_f32 v[228:231], v136, v116, 0
	v_mfma_f32_16x16x4_f32 v[228:231], v137, v117, v[228:231]
	v_mfma_f32_16x16x4_f32 v[228:231], v138, v118, v[228:231]
	v_mfma_f32_16x16x4_f32 v[228:231], v139, v119, v[228:231]
	v_mfma_f32_16x16x4_f32 v[228:231], v140, v120, v[228:231]
	v_mfma_f32_16x16x4_f32 v[228:231], v141, v121, v[228:231]
	v_mfma_f32_16x16x4_f32 v[228:231], v142, v122, v[228:231]
	v_mfma_f32_16x16x4_f32 v[228:231], v143, v123, v[228:231]
	v_mfma_f32_16x16x4_f32 v[228:231], v144, v124, v[228:231]
	v_mfma_f32_16x16x4_f32 v[228:231], v145, v125, v[228:231]
	v_mfma_f32_16x16x4_f32 v[228:231], v146, v126, v[228:231]
	v_mfma_f32_16x16x4_f32 v[228:231], v147, v127, v[228:231]
	v_mfma_f32_16x16x4_f32 v[228:231], v148, v128, v[228:231]
	v_mfma_f32_16x16x4_f32 v[228:231], v149, v129, v[228:231]
	v_mfma_f32_16x16x4_f32 v[228:231], v150, v130, v[228:231]
	v_mfma_f32_16x16x4_f32 v[228:231], v151, v131, v[228:231]
	s_cmp_lt_u32 s0, 2
	s_cbranch_scc1 .Lmqk_md
	v_add_u32_e32 v36, 0xffffdf80, v28
	ds_read2_b32 v[116:117], v36 offset0:0 offset1:4
	ds_read2_b32 v[118:119], v36 offset0:8 offset1:12
	ds_read2_b32 v[120:121], v36 offset0:16 offset1:20
	ds_read2_b32 v[122:123], v36 offset0:24 offset1:28
	ds_read2_b32 v[124:125], v36 offset0:32 offset1:36
	ds_read2_b32 v[126:127], v36 offset0:40 offset1:44
	ds_read2_b32 v[128:129], v36 offset0:48 offset1:52
	ds_read2_b32 v[130:131], v36 offset0:56 offset1:60
	s_waitcnt lgkmcnt(0)
	v_mfma_f32_16x16x4_f32 v[236:239], v136, v116, 0
	v_mfma_f32_16x16x4_f32 v[236:239], v137, v117, v[236:239]
	v_mfma_f32_16x16x4_f32 v[236:239], v138, v118, v[236:239]
	v_mfma_f32_16x16x4_f32 v[236:239], v139, v119, v[236:239]
	v_mfma_f32_16x16x4_f32 v[236:239], v140, v120, v[236:239]
	v_mfma_f32_16x16x4_f32 v[236:239], v141, v121, v[236:239]
	v_mfma_f32_16x16x4_f32 v[236:239], v142, v122, v[236:239]
	v_mfma_f32_16x16x4_f32 v[236:239], v143, v123, v[236:239]
	v_mfma_f32_16x16x4_f32 v[236:239], v144, v124, v[236:239]
	v_mfma_f32_16x16x4_f32 v[236:239], v145, v125, v[236:239]
	v_mfma_f32_16x16x4_f32 v[236:239], v146, v126, v[236:239]
	v_mfma_f32_16x16x4_f32 v[236:239], v147, v127, v[236:239]
	v_mfma_f32_16x16x4_f32 v[236:239], v148, v128, v[236:239]
	v_mfma_f32_16x16x4_f32 v[236:239], v149, v129, v[236:239]
	v_mfma_f32_16x16x4_f32 v[236:239], v150, v130, v[236:239]
	v_mfma_f32_16x16x4_f32 v[236:239], v151, v131, v[236:239]
	s_cmp_lt_u32 s0, 3
	s_cbranch_scc1 .Lmqk_md
	v_add_u32_e32 v36, 0xffffcf40, v28
	ds_read2_b32 v[116:117], v36 offset0:0 offset1:4
	ds_read2_b32 v[118:119], v36 offset0:8 offset1:12
	ds_read2_b32 v[120:121], v36 offset0:16 offset1:20
	ds_read2_b32 v[122:123], v36 offset0:24 offset1:28
	ds_read2_b32 v[124:125], v36 offset0:32 offset1:36
	ds_read2_b32 v[126:127], v36 offset0:40 offset1:44
	ds_read2_b32 v[128:129], v36 offset0:48 offset1:52
	ds_read2_b32 v[130:131], v36 offset0:56 offset1:60
	s_waitcnt lgkmcnt(0)
	v_mfma_f32_16x16x4_f32 v[240:243], v136, v116, 0
	v_mfma_f32_16x16x4_f32 v[240:243], v137, v117, v[240:243]
	v_mfma_f32_16x16x4_f32 v[240:243], v138, v118, v[240:243]
	v_mfma_f32_16x16x4_f32 v[240:243], v139, v119, v[240:243]
	v_mfma_f32_16x16x4_f32 v[240:243], v140, v120, v[240:243]
	v_mfma_f32_16x16x4_f32 v[240:243], v141, v121, v[240:243]
	v_mfma_f32_16x16x4_f32 v[240:243], v142, v122, v[240:243]
	v_mfma_f32_16x16x4_f32 v[240:243], v143, v123, v[240:243]
	v_mfma_f32_16x16x4_f32 v[240:243], v144, v124, v[240:243]
	v_mfma_f32_16x16x4_f32 v[240:243], v145, v125, v[240:243]
	v_mfma_f32_16x16x4_f32 v[240:243], v146, v126, v[240:243]
	v_mfma_f32_16x16x4_f32 v[240:243], v147, v127, v[240:243]
	v_mfma_f32_16x16x4_f32 v[240:243], v148, v128, v[240:243]
	v_mfma_f32_16x16x4_f32 v[240:243], v149, v129, v[240:243]
	v_mfma_f32_16x16x4_f32 v[240:243], v150, v130, v[240:243]
	v_mfma_f32_16x16x4_f32 v[240:243], v151, v131, v[240:243]
.Lmqk_md:
	s_nop 7
	s_nop 3
	v_add_u32_e32 v38, v34, v37
	ds_write_b32 v38, v224 offset:0
	ds_write_b32 v38, v225 offset:256
	ds_write_b32 v38, v226 offset:512
	ds_write_b32 v38, v227 offset:768
	s_cmp_lt_u32 s0, 1
	s_cbranch_scc1 .Lmqk_w
	v_add_u32_e32 v38, v34, v37
	v_add_u32_e32 v38, 0xffffffc0, v38
	ds_write_b32 v38, v228 offset:0
	ds_write_b32 v38, v229 offset:256
	ds_write_b32 v38, v230 offset:512
	ds_write_b32 v38, v231 offset:768
	s_cmp_lt_u32 s0, 2
	s_cbranch_scc1 .Lmqk_w
	v_add_u32_e32 v38, v34, v37
	v_add_u32_e32 v38, 0xffffff80, v38
	ds_write_b32 v38, v236 offset:0
	ds_write_b32 v38, v237 offset:256
	ds_write_b32 v38, v238 offset:512
	ds_write_b32 v38, v239 offset:768
	s_cmp_lt_u32 s0, 3
	s_cbranch_scc1 .Lmqk_w
	v_add_u32_e32 v38, v34, v37
	v_add_u32_e32 v38, 0xffffff40, v38
	ds_write_b32 v38, v240 offset:0
	ds_write_b32 v38, v241 offset:256
	ds_write_b32 v38, v242 offset:512
	ds_write_b32 v38, v243 offset:768
.Lmqk_w:
	s_cmp_gt_u32 s0, 2
	s_cbranch_scc1 .Lmqk_z
	v_add_u32_e32 v38, v34, v37
	v_add_u32_e32 v38, 0x40, v38
	ds_write_b32 v38, v113 offset:0
	ds_write_b32 v38, v113 offset:256
	ds_write_b32 v38, v113 offset:512
	ds_write_b32 v38, v113 offset:768
	s_cmp_gt_u32 s0, 1
	s_cbranch_scc1 .Lmqk_z
	v_add_u32_e32 v38, v34, v37
	v_add_u32_e32 v38, 0x80, v38
	ds_write_b32 v38, v113 offset:0
	ds_write_b32 v38, v113 offset:256
	ds_write_b32 v38, v113 offset:512
	ds_write_b32 v38, v113 offset:768
	s_cmp_gt_u32 s0, 0
	s_cbranch_scc1 .Lmqk_z
	v_add_u32_e32 v38, v34, v37
	v_add_u32_e32 v38, 0xc0, v38
	ds_write_b32 v38, v113 offset:0
	ds_write_b32 v38, v113 offset:256
	ds_write_b32 v38, v113 offset:512
	ds_write_b32 v38, v113 offset:768
.Lmqk_z:
	s_waitcnt lgkmcnt(0)
	ds_read_b128 v[116:119], v35 offset:0
	ds_read_b128 v[120:123], v35 offset:256
	ds_read_b128 v[124:127], v35 offset:512
	ds_read_b128 v[128:131], v35 offset:768
	s_waitcnt lgkmcnt(0)
	v_mov_b32_e32 v17, v116
	v_mov_b32_e32 v16, v117
	v_mov_b32_e32 v14, v118
	v_mov_b32_e32 v15, v119
	v_mov_b32_e32 v13, v120
	v_mov_b32_e32 v12, v121
	v_mov_b32_e32 v11, v122
	v_mov_b32_e32 v10, v123
	v_mov_b32_e32 v9, v124
	v_mov_b32_e32 v8, v125
	v_mov_b32_e32 v7, v126
	v_mov_b32_e32 v6, v127
	v_mov_b32_e32 v5, v128
	v_mov_b32_e32 v4, v129
	v_mov_b32_e32 v3, v130
	v_mov_b32_e32 v2, v131
